# residual GEMM: first half of the bf16 residual tile loaded into spare registers at unit start instead of in the epilogue
# baseline (speedup 1.0000x reference)
.LBB0_1471:
	s_mul_i32 s100, s62, 0xc0
	s_add_i32 s100, s100, s56
	v_lshl_or_b32 v204, s33, 8, v118
	v_ashrrev_i32_e32 v205, 31, v204
	v_or_b32_e32 v207, s100, v1
	v_lshlrev_b64 v[204:205], 1, v[204:205]
	v_mov_b32_e32 v232, v207
	v_lshl_add_u64 v[204:205], s[20:21], 0, v[204:205]
	v_ashrrev_i32_e32 v233, 31, v232
	v_or_b32_e32 v240, 16, v207
	v_lshlrev_b64 v[232:233], 12, v[232:233]
	v_ashrrev_i32_e32 v241, 31, v240
	v_lshl_add_u64 v[232:233], v[204:205], 0, v[232:233]
	v_lshlrev_b64 v[240:241], 12, v[240:241]
	v_or_b32_e32 v242, 32, v207
	global_load_dwordx4 v[192:195], v[232:233], off
	v_lshl_add_u64 v[240:241], v[204:205], 0, v[240:241]
	global_load_dwordx4 v[196:199], v[232:233], off offset:256
	v_ashrrev_i32_e32 v243, 31, v242
	v_or_b32_e32 v232, 48, v207
	global_load_dwordx4 v[208:211], v[240:241], off
	v_lshlrev_b64 v[242:243], 12, v[242:243]
	global_load_dwordx4 v[212:215], v[240:241], off offset:256
	v_ashrrev_i32_e32 v233, 31, v232
	v_lshl_add_u64 v[242:243], v[204:205], 0, v[242:243]
	v_lshlrev_b64 v[232:233], 12, v[232:233]
	s_nop 0
	global_load_dwordx4 v[216:219], v[242:243], off
	v_lshl_add_u64 v[232:233], v[204:205], 0, v[232:233]
	global_load_dwordx4 v[220:223], v[242:243], off offset:256
	s_nop 0
	global_load_dwordx4 v[224:227], v[232:233], off
	global_load_dwordx4 v[228:231], v[232:233], off offset:256
	s_add_i32 s59, s59, 1
	v_readlane_b32 s14, v251, 62
	s_mul_i32 s14, s59, s14
	s_mul_hi_u32 s15, s59, s97
	s_add_i32 s15, s15, s14
	s_mul_i32 s14, s59, s97
	s_add_u32 s14, s14, s95
	s_addc_u32 s15, s15, s96
	v_cmp_gt_i64_e32 vcc, s[14:15], v[202:203]
	v_cmp_lt_i64_e64 s[50:51], s[14:15], v[200:201]
	s_cbranch_vccnz .LBB0_1477
	s_ashr_i32 s15, s14, 31
	s_lshr_b32 s15, s15, 29
	s_add_i32 s42, s14, s15
	s_and_b32 s15, s42, -8
	s_sub_i32 s43, s14, s15
	s_cmp_gt_i32 s43, -1
	s_mov_b64 s[14:15], -1
	s_cbranch_scc0 .LBB0_1474
	s_lshl_b32 s44, s43, 6
	s_mov_b64 s[14:15], 0

.LBB0_1485:
	s_mul_i32 s12, s62, 0xc0
	s_add_i32 s13, s12, s56
	s_add_i32 s14, s13, 0xfffff000
	s_lshr_b32 s14, s14, 10
	v_lshl_or_b32 v114, s33, 8, v118
	s_add_i32 s14, s14, 1
	v_ashrrev_i32_e32 v115, 31, v114
	v_or_b32_e32 v116, s13, v1
	s_cmpk_gt_i32 s13, 0xfff
	v_lshlrev_b64 v[110:111], 1, v[114:115]
	v_ashrrev_i32_e32 v117, 31, v116
	v_or_b32_e32 v130, 16, v116
	s_cselect_b32 s13, s14, 0
	v_lshl_add_u64 v[112:113], s[20:21], 0, v[110:111]
	v_lshlrev_b64 v[154:155], 12, v[116:117]
	v_ashrrev_i32_e32 v131, 31, v130
	s_mul_hi_u32 s15, s13, 0x12000
	s_mul_i32 s13, s13, 0x12000
	v_lshl_add_u64 v[126:127], v[112:113], 0, v[154:155]
	v_lshlrev_b64 v[170:171], 12, v[130:131]
	s_add_u32 s14, s47, s13
	s_nop 0
	v_lshlrev_b64 v[114:115], 2, v[114:115]
	v_lshl_add_u64 v[150:151], v[112:113], 0, v[170:171]
	s_addc_u32 s15, s52, s15
	s_nop 0
	v_lshl_add_u64 v[146:147], s[14:15], 0, v[114:115]
	s_nop 0
	s_nop 0
	global_load_dwordx4 v[134:137], v[146:147], off
	global_load_dwordx4 v[138:141], v[146:147], off offset:16
	global_load_dwordx4 v[142:145], v[146:147], off offset:512
	s_nop 0
	global_load_dwordx4 v[146:149], v[146:147], off offset:528
	s_nop 0
	s_nop 0
	v_or_b32_e32 v156, 32, v116
	v_or_b32_e32 v116, 48, v116
	v_ashrrev_i32_e32 v157, 31, v156
	v_ashrrev_i32_e32 v117, 31, v116
	v_lshlrev_b64 v[172:173], 12, v[156:157]
	v_lshlrev_b64 v[116:117], 12, v[116:117]
	v_lshl_add_u64 v[154:155], s[20:21], 0, v[154:155]
	v_lshl_add_u64 v[158:159], v[112:113], 0, v[172:173]
	v_lshl_add_u64 v[166:167], v[112:113], 0, v[116:117]
	v_lshl_add_u64 v[174:175], v[154:155], 0, v[110:111]
	s_nop 0
	s_nop 0
	s_nop 0
	s_nop 0
	s_nop 0
	s_nop 0
	s_nop 0
	s_add_i32 s14, s58, s12
	s_add_i32 s12, s14, 0xfffff000
	s_lshr_b32 s12, s12, 10
	s_add_i32 s12, s12, 1
	s_cmpk_gt_i32 s14, 0xfff
	s_cselect_b32 s12, s12, 0
	s_mul_hi_u32 s13, s12, 0x12000
	s_mul_i32 s12, s12, 0x12000
	s_add_u32 s12, s47, s12
	s_addc_u32 s13, s52, s13
	s_and_b64 vcc, exec, s[48:49]
	s_waitcnt vmcnt(0)
	v_mov_b64_e32 v[122:123], v[192:193]
	v_mov_b64_e32 v[124:125], v[194:195]
	v_mov_b64_e32 v[130:131], v[208:209]
	v_mov_b64_e32 v[132:133], v[210:211]
	v_mov_b64_e32 v[126:127], v[196:197]
	v_mov_b64_e32 v[128:129], v[198:199]
	v_mov_b64_e32 v[150:151], v[212:213]
	v_mov_b64_e32 v[152:153], v[214:215]
	v_mov_b64_e32 v[154:155], v[216:217]
	v_mov_b64_e32 v[156:157], v[218:219]
	v_mov_b64_e32 v[158:159], v[220:221]
	v_mov_b64_e32 v[160:161], v[222:223]
	v_mov_b64_e32 v[162:163], v[224:225]
	v_mov_b64_e32 v[164:165], v[226:227]
	v_mov_b64_e32 v[166:167], v[228:229]
	v_mov_b64_e32 v[168:169], v[230:231]
	v_lshlrev_b32_e32 v176, 16, v122
	v_and_b32_e32 v177, 0xffff0000, v122
	v_lshlrev_b32_e32 v122, 16, v123
	v_and_b32_e32 v123, 0xffff0000, v123
	v_lshlrev_b32_e32 v178, 16, v124
	v_and_b32_e32 v179, 0xffff0000, v124
	v_lshlrev_b32_e32 v124, 16, v125
	v_and_b32_e32 v125, 0xffff0000, v125
	v_pk_mul_f32 v[136:137], s[24:25], v[136:137]
	v_pk_mul_f32 v[134:135], s[10:11], v[134:135]
	v_pk_mul_f32 v[140:141], s[24:25], v[140:141]
	v_pk_mul_f32 v[138:139], s[10:11], v[138:139]
	v_lshlrev_b32_e32 v180, 16, v126
	v_and_b32_e32 v181, 0xffff0000, v126
	v_lshlrev_b32_e32 v126, 16, v127
	v_and_b32_e32 v127, 0xffff0000, v127
	v_lshlrev_b32_e32 v182, 16, v128
	v_and_b32_e32 v183, 0xffff0000, v128
	v_lshlrev_b32_e32 v128, 16, v129
	v_and_b32_e32 v129, 0xffff0000, v129
	v_pk_mul_f32 v[144:145], s[24:25], v[144:145]
	v_pk_mul_f32 v[142:143], s[10:11], v[142:143]
	v_pk_mul_f32 v[148:149], s[24:25], v[148:149]
	v_pk_mul_f32 v[146:147], s[10:11], v[146:147]
	v_pk_fma_f32 v[102:103], v[102:103], v[136:137], v[122:123]
	v_pk_fma_f32 v[100:101], v[100:101], v[134:135], v[176:177]
	v_pk_fma_f32 v[98:99], v[98:99], v[140:141], v[124:125]
	v_pk_fma_f32 v[96:97], v[96:97], v[138:139], v[178:179]
	v_pk_fma_f32 v[90:91], v[90:91], v[144:145], v[126:127]
	v_pk_fma_f32 v[88:89], v[88:89], v[142:143], v[180:181]
	v_pk_fma_f32 v[122:123], v[86:87], v[148:149], v[128:129]
	v_pk_fma_f32 v[124:125], v[84:85], v[146:147], v[182:183]
	v_cvt_pk_bf16_f32 v84, v100, v101
	v_cvt_pk_bf16_f32 v85, v102, v103
	v_cvt_pk_bf16_f32 v86, v96, v97
	v_cvt_pk_bf16_f32 v87, v98, v99
	v_lshlrev_b32_e32 v186, 16, v132
	v_and_b32_e32 v187, 0xffff0000, v132
	v_cvt_pk_bf16_f32 v88, v88, v89
	v_cvt_pk_bf16_f32 v89, v90, v91
	v_cvt_pk_bf16_f32 v90, v124, v125
	v_cvt_pk_bf16_f32 v91, v122, v123
	global_store_dwordx4 v[174:175], v[84:87], off
	global_store_dwordx4 v[174:175], v[88:91], off offset:256
	v_lshlrev_b32_e32 v184, 16, v130
	v_lshlrev_b32_e32 v84, 16, v133
	v_and_b32_e32 v85, 0xffff0000, v133
	v_and_b32_e32 v185, 0xffff0000, v130
	v_lshlrev_b32_e32 v130, 16, v131
	v_and_b32_e32 v131, 0xffff0000, v131
	v_pk_fma_f32 v[84:85], v[82:83], v[140:141], v[84:85]
	v_pk_fma_f32 v[82:83], v[80:81], v[138:139], v[186:187]
	v_pk_fma_f32 v[86:87], v[94:95], v[136:137], v[130:131]
	v_pk_fma_f32 v[88:89], v[92:93], v[134:135], v[184:185]
	v_cvt_pk_bf16_f32 v82, v82, v83
	v_cvt_pk_bf16_f32 v83, v84, v85
	v_lshl_add_u64 v[84:85], s[20:21], 0, v[170:171]
	v_cvt_pk_bf16_f32 v80, v88, v89
	v_cvt_pk_bf16_f32 v81, v86, v87
	v_lshl_add_u64 v[84:85], v[84:85], 0, v[110:111]
	global_store_dwordx4 v[84:85], v[80:83], off
	v_lshlrev_b32_e32 v86, 16, v152
	v_and_b32_e32 v87, 0xffff0000, v152
	v_lshlrev_b32_e32 v80, 16, v150
	v_and_b32_e32 v81, 0xffff0000, v150
	v_lshlrev_b32_e32 v82, 16, v151
	v_and_b32_e32 v83, 0xffff0000, v151
	v_lshlrev_b32_e32 v88, 16, v153
	v_and_b32_e32 v89, 0xffff0000, v153
	v_pk_fma_f32 v[78:79], v[78:79], v[144:145], v[82:83]
	v_pk_fma_f32 v[76:77], v[76:77], v[142:143], v[80:81]
	v_pk_fma_f32 v[80:81], v[70:71], v[148:149], v[88:89]
	v_pk_fma_f32 v[70:71], v[68:69], v[146:147], v[86:87]
	v_cvt_pk_bf16_f32 v68, v76, v77
	v_cvt_pk_bf16_f32 v69, v78, v79
	v_cvt_pk_bf16_f32 v70, v70, v71
	v_cvt_pk_bf16_f32 v71, v80, v81
	global_store_dwordx4 v[84:85], v[68:71], off offset:256
	v_lshlrev_b32_e32 v76, 16, v156
	v_and_b32_e32 v77, 0xffff0000, v156
	v_lshlrev_b32_e32 v68, 16, v154
	v_and_b32_e32 v69, 0xffff0000, v154
	v_lshlrev_b32_e32 v70, 16, v155
	v_and_b32_e32 v71, 0xffff0000, v155
	v_lshlrev_b32_e32 v78, 16, v157
	v_and_b32_e32 v79, 0xffff0000, v157
	v_pk_fma_f32 v[68:69], v[72:73], v[134:135], v[68:69]
	v_pk_fma_f32 v[70:71], v[74:75], v[136:137], v[70:71]
	v_pk_fma_f32 v[72:73], v[66:67], v[140:141], v[78:79]
	v_pk_fma_f32 v[66:67], v[64:65], v[138:139], v[76:77]
	v_cvt_pk_bf16_f32 v64, v68, v69
	v_lshl_add_u64 v[68:69], s[20:21], 0, v[172:173]
	v_cvt_pk_bf16_f32 v65, v70, v71
	v_cvt_pk_bf16_f32 v66, v66, v67
	v_cvt_pk_bf16_f32 v67, v72, v73
	v_lshl_add_u64 v[68:69], v[68:69], 0, v[110:111]
	global_store_dwordx4 v[68:69], v[64:67], off
	v_lshlrev_b32_e32 v70, 16, v160
	v_and_b32_e32 v71, 0xffff0000, v160
	v_lshlrev_b32_e32 v64, 16, v158
	v_and_b32_e32 v65, 0xffff0000, v158
	v_lshlrev_b32_e32 v66, 16, v159
	v_and_b32_e32 v67, 0xffff0000, v159
	v_lshlrev_b32_e32 v72, 16, v161
	v_and_b32_e32 v73, 0xffff0000, v161
	v_pk_fma_f32 v[62:63], v[62:63], v[144:145], v[66:67]
	v_pk_fma_f32 v[60:61], v[60:61], v[142:143], v[64:65]
	v_pk_fma_f32 v[64:65], v[54:55], v[148:149], v[72:73]
	v_pk_fma_f32 v[54:55], v[52:53], v[146:147], v[70:71]
	v_cvt_pk_bf16_f32 v52, v60, v61
	v_cvt_pk_bf16_f32 v53, v62, v63
	v_cvt_pk_bf16_f32 v54, v54, v55
	v_cvt_pk_bf16_f32 v55, v64, v65
	global_store_dwordx4 v[68:69], v[52:55], off offset:256
	v_lshlrev_b32_e32 v60, 16, v164
	v_and_b32_e32 v61, 0xffff0000, v164
	v_lshlrev_b32_e32 v52, 16, v162
	v_and_b32_e32 v53, 0xffff0000, v162
	v_lshlrev_b32_e32 v54, 16, v163
	v_and_b32_e32 v55, 0xffff0000, v163
	v_lshlrev_b32_e32 v62, 16, v165
	v_and_b32_e32 v63, 0xffff0000, v165
	v_pk_fma_f32 v[52:53], v[56:57], v[134:135], v[52:53]
	v_pk_fma_f32 v[54:55], v[58:59], v[136:137], v[54:55]
	v_pk_fma_f32 v[56:57], v[50:51], v[140:141], v[62:63]
	v_pk_fma_f32 v[50:51], v[48:49], v[138:139], v[60:61]
	v_cvt_pk_bf16_f32 v48, v52, v53
	v_lshl_add_u64 v[52:53], s[20:21], 0, v[116:117]
	v_cvt_pk_bf16_f32 v49, v54, v55
	v_cvt_pk_bf16_f32 v50, v50, v51
	v_cvt_pk_bf16_f32 v51, v56, v57
	v_lshl_add_u64 v[52:53], v[52:53], 0, v[110:111]
	global_store_dwordx4 v[52:53], v[48:51], off
	v_lshlrev_b32_e32 v54, 16, v168
	v_and_b32_e32 v55, 0xffff0000, v168
	v_lshlrev_b32_e32 v48, 16, v166
	v_and_b32_e32 v49, 0xffff0000, v166
	v_lshlrev_b32_e32 v50, 16, v167
	v_and_b32_e32 v51, 0xffff0000, v167
	v_lshlrev_b32_e32 v56, 16, v169
	v_and_b32_e32 v57, 0xffff0000, v169
	v_or_b32_e32 v64, s14, v1
	v_pk_fma_f32 v[46:47], v[46:47], v[144:145], v[50:51]
	v_pk_fma_f32 v[44:45], v[44:45], v[142:143], v[48:49]
	v_pk_fma_f32 v[48:49], v[42:43], v[148:149], v[56:57]
	v_pk_fma_f32 v[42:43], v[40:41], v[146:147], v[54:55]
	v_ashrrev_i32_e32 v65, 31, v64
	v_cvt_pk_bf16_f32 v40, v44, v45
	v_cvt_pk_bf16_f32 v41, v46, v47
	v_cvt_pk_bf16_f32 v42, v42, v43
	v_cvt_pk_bf16_f32 v43, v48, v49
	v_lshlrev_b64 v[72:73], 12, v[64:65]
	global_store_dwordx4 v[52:53], v[40:43], off offset:256
	v_lshl_add_u64 v[52:53], s[12:13], 0, v[114:115]
	v_lshl_add_u64 v[60:61], v[112:113], 0, v[72:73]
	global_load_dwordx4 v[40:43], v[52:53], off
	global_load_dwordx4 v[44:47], v[52:53], off offset:16
	global_load_dwordx4 v[48:51], v[52:53], off offset:528
	s_nop 0
	global_load_dwordx4 v[52:55], v[52:53], off offset:512
	s_nop 0
	global_load_dwordx4 v[56:59], v[60:61], off
	s_nop 0
	global_load_dwordx4 v[60:63], v[60:61], off offset:256
	v_or_b32_e32 v64, 16, v64
	v_ashrrev_i32_e32 v65, 31, v64
	v_lshlrev_b64 v[74:75], 12, v[64:65]
	v_lshl_add_u64 v[68:69], v[112:113], 0, v[74:75]
	global_load_dwordx4 v[64:67], v[68:69], off
	s_nop 0
	global_load_dwordx4 v[68:71], v[68:69], off offset:256
	s_mov_b64 s[12:13], -1
	s_waitcnt vmcnt(7)
	v_pk_mul_f32 v[40:41], s[10:11], v[40:41]
	v_pk_mul_f32 v[42:43], s[24:25], v[42:43]
	s_waitcnt vmcnt(6)
	v_pk_mul_f32 v[46:47], s[24:25], v[46:47]
	s_waitcnt vmcnt(3)
	v_lshlrev_b32_e32 v76, 16, v56
	v_and_b32_e32 v77, 0xffff0000, v56
	v_pk_mul_f32 v[44:45], s[10:11], v[44:45]
	v_lshlrev_b32_e32 v56, 16, v57
	v_and_b32_e32 v57, 0xffff0000, v57
	v_lshlrev_b32_e32 v78, 16, v58
	v_and_b32_e32 v79, 0xffff0000, v58
	v_lshlrev_b32_e32 v58, 16, v59
	v_and_b32_e32 v59, 0xffff0000, v59
	v_pk_fma_f32 v[36:37], v[36:37], v[40:41], v[76:77]
	v_pk_fma_f32 v[38:39], v[38:39], v[42:43], v[56:57]
	v_pk_fma_f32 v[56:57], v[34:35], v[46:47], v[58:59]
	v_pk_fma_f32 v[34:35], v[32:33], v[44:45], v[78:79]
	v_cvt_pk_bf16_f32 v32, v36, v37
	v_lshl_add_u64 v[36:37], s[20:21], 0, v[72:73]
	v_cvt_pk_bf16_f32 v33, v38, v39
	v_cvt_pk_bf16_f32 v34, v34, v35
	v_cvt_pk_bf16_f32 v35, v56, v57
	v_lshl_add_u64 v[36:37], v[36:37], 0, v[110:111]
	v_pk_mul_f32 v[54:55], s[24:25], v[54:55]
	v_pk_mul_f32 v[52:53], s[10:11], v[52:53]
	v_pk_mul_f32 v[50:51], s[24:25], v[50:51]
	v_pk_mul_f32 v[48:49], s[10:11], v[48:49]
	global_store_dwordx4 v[36:37], v[32:35], off
	s_waitcnt vmcnt(3)
	v_lshlrev_b32_e32 v38, 16, v62
	v_and_b32_e32 v39, 0xffff0000, v62
	v_lshlrev_b32_e32 v32, 16, v60
	v_and_b32_e32 v33, 0xffff0000, v60
	v_lshlrev_b32_e32 v34, 16, v61
	v_and_b32_e32 v35, 0xffff0000, v61
	v_lshlrev_b32_e32 v56, 16, v63
	v_and_b32_e32 v57, 0xffff0000, v63
	v_pk_fma_f32 v[30:31], v[30:31], v[54:55], v[34:35]
	v_pk_fma_f32 v[28:29], v[28:29], v[52:53], v[32:33]
	v_pk_fma_f32 v[32:33], v[26:27], v[50:51], v[56:57]
	v_pk_fma_f32 v[26:27], v[24:25], v[48:49], v[38:39]
	v_cvt_pk_bf16_f32 v24, v28, v29
	v_cvt_pk_bf16_f32 v25, v30, v31
	v_cvt_pk_bf16_f32 v26, v26, v27
	v_cvt_pk_bf16_f32 v27, v32, v33
	global_store_dwordx4 v[36:37], v[24:27], off offset:256
	s_waitcnt vmcnt(3)
	v_lshlrev_b32_e32 v28, 16, v66
	v_and_b32_e32 v29, 0xffff0000, v66
	v_lshlrev_b32_e32 v24, 16, v64
	v_and_b32_e32 v25, 0xffff0000, v64
	v_lshlrev_b32_e32 v26, 16, v65
	v_and_b32_e32 v27, 0xffff0000, v65
	v_lshlrev_b32_e32 v30, 16, v67
	v_and_b32_e32 v31, 0xffff0000, v67
	v_pk_fma_f32 v[20:21], v[20:21], v[40:41], v[24:25]
	v_pk_fma_f32 v[22:23], v[22:23], v[42:43], v[26:27]
	v_pk_fma_f32 v[24:25], v[18:19], v[46:47], v[30:31]
	v_pk_fma_f32 v[18:19], v[16:17], v[44:45], v[28:29]
	v_cvt_pk_bf16_f32 v16, v20, v21
	v_lshl_add_u64 v[20:21], s[20:21], 0, v[74:75]
	v_cvt_pk_bf16_f32 v17, v22, v23
	v_cvt_pk_bf16_f32 v18, v18, v19
	v_cvt_pk_bf16_f32 v19, v24, v25
	v_lshl_add_u64 v[20:21], v[20:21], 0, v[110:111]
	global_store_dwordx4 v[20:21], v[16:19], off
	s_waitcnt vmcnt(3)
	v_lshlrev_b32_e32 v22, 16, v70
	v_and_b32_e32 v23, 0xffff0000, v70
	v_lshlrev_b32_e32 v16, 16, v68
	v_and_b32_e32 v17, 0xffff0000, v68
	v_lshlrev_b32_e32 v18, 16, v69
	v_and_b32_e32 v19, 0xffff0000, v69
	v_lshlrev_b32_e32 v24, 16, v71
	v_and_b32_e32 v25, 0xffff0000, v71
	v_pk_fma_f32 v[14:15], v[14:15], v[54:55], v[18:19]
	v_pk_fma_f32 v[12:13], v[12:13], v[52:53], v[16:17]
	v_pk_fma_f32 v[16:17], v[10:11], v[50:51], v[24:25]
	v_pk_fma_f32 v[10:11], v[8:9], v[48:49], v[22:23]
	v_cvt_pk_bf16_f32 v8, v12, v13
	v_cvt_pk_bf16_f32 v9, v14, v15
	v_cvt_pk_bf16_f32 v10, v10, v11
	v_cvt_pk_bf16_f32 v11, v16, v17
	global_store_dwordx4 v[20:21], v[8:11], off offset:256
	s_cbranch_vccnz .LBB0_1470
	s_andn2_b64 vcc, exec, s[16:17]
	s_cbranch_vccnz .LBB0_1469
	s_barrier
	s_branch .LBB0_1469
